# adds hand-written initial input conversion (round 0) and hand-written memory-row normalisation (16B accesses, gains resident, no waits between stores)
# baseline (speedup 1.0000x reference)
; DI unsigned pk2(float lo, float hi) { return pg8::cvt_pk_bf16(lo, hi); }
; DI void prologue(const Params& P, LAS unsigned char* lds) {
;     ...
;     bf16* memn = (bf16*)(ws + WS_MEMN);
;     for (int row = gw; row < MEMROWS; row += NGW) {
;         const float* src = row < 4096 ? P.mem_prompt + (size_t)row * D : P.mem_sample + (size_t)(row - 4096) * D;
;         f32x4 v[8]; float ss = 0.f;
; #pragma unroll
;         for (int j = 0; j < 8; ++j) { v[j] = ((const f32x4*)src)[lane + 64 * j]; ss += (v[j].x * v[j].x + v[j].y * v[j].y) + (v[j].z * v[j].z + v[j].w * v[j].w); }
;         const float rstd = 1.0f / sqrtf(wave_sum(ss) * (1.0f / D) + EPS);
; #pragma unroll
;         for (int i = 0; i < 2; ++i)
; #pragma unroll
;             for (int j = 0; j < 8; ++j) { const f32x4 g = ((const f32x4*)(P.mem_norm_gain + i * D))[lane + 64 * j]; const f32x4 o = v[j] * rstd * g;
;                 v2u w; w.x = pk2(o.x, o.y); w.y = pk2(o.z, o.w); ((v2u*)(memn + ((size_t)i * MEMROWS + row) * D))[lane + 64 * j] = w; }
;     }
.LBB0_107:
	s_or_b64 exec, exec, s[16:17]
	s_load_dwordx2 s[6:7], s[84:85], 0x0
	s_cmpk_gt_i32 s30, 0x13ff
	v_mbcnt_lo_u32_b32 v1, -1, 0
	s_cbranch_scc1 .LBB0_112
	v_lshlrev_b32_e32 v100, 5, v34
	v_lshlrev_b32_e32 v102, 4, v34
	v_add_u32_e32 v101, 0x1000, v100
	s_add_u32 s2, s54, 0xc700000
	s_addc_u32 s3, s55, 0
	s_mov_b32 s16, 0x3a000000
	s_mov_b32 s17, 0x358637bd
	s_mov_b32 s4, s30
	s_add_u32 s0, s18, 0
	s_addc_u32 s1, s19, 0
	global_load_dwordx4 v[36:39], v100, s[0:1]
	global_load_dwordx4 v[40:43], v100, s[0:1] offset:16
	global_load_dwordx4 v[44:47], v100, s[0:1] offset:2048
	global_load_dwordx4 v[48:51], v100, s[0:1] offset:2064
	global_load_dwordx4 v[52:55], v101, s[0:1]
	global_load_dwordx4 v[56:59], v101, s[0:1] offset:16
	global_load_dwordx4 v[60:63], v101, s[0:1] offset:2048
	global_load_dwordx4 v[64:67], v101, s[0:1] offset:2064
	s_add_u32 s0, s18, 8192
	s_addc_u32 s1, s19, 0
	global_load_dwordx4 v[68:71], v100, s[0:1]
	global_load_dwordx4 v[72:75], v100, s[0:1] offset:16
	global_load_dwordx4 v[76:79], v100, s[0:1] offset:2048
	global_load_dwordx4 v[80:83], v100, s[0:1] offset:2064
	global_load_dwordx4 v[84:87], v101, s[0:1]
	global_load_dwordx4 v[88:91], v101, s[0:1] offset:16
	global_load_dwordx4 v[92:95], v101, s[0:1] offset:2048
	global_load_dwordx4 v[96:99], v101, s[0:1] offset:2064
.Lmr_top:
	s_cmpk_lt_u32 s4, 0x1000
	s_cbranch_scc0 .Lmr_sample
	s_lshl_b32 s5, s4, 13
	s_add_u32 s0, s12, s5
	s_addc_u32 s1, s13, 0
	s_branch .Lmr_load
.Lmr_sample:
	s_sub_u32 s5, s4, 0x1000
	s_lshl_b32 s5, s5, 13
	s_add_u32 s0, s14, s5
	s_addc_u32 s1, s15, 0
.Lmr_load:
	global_load_dwordx4 v[2:5], v100, s[0:1]
	global_load_dwordx4 v[6:9], v100, s[0:1] offset:16
	global_load_dwordx4 v[10:13], v100, s[0:1] offset:2048
	global_load_dwordx4 v[14:17], v100, s[0:1] offset:2064
	global_load_dwordx4 v[18:21], v101, s[0:1]
	global_load_dwordx4 v[22:25], v101, s[0:1] offset:16
	global_load_dwordx4 v[26:29], v101, s[0:1] offset:2048
	global_load_dwordx4 v[30:33], v101, s[0:1] offset:2064
	v_mov_b32_e32 v103, 0
	v_mov_b32_e32 v104, 0
	v_mov_b32_e32 v105, 0
	v_mov_b32_e32 v106, 0
	s_waitcnt vmcnt(0)
	v_fmac_f32_e32 v103, v2, v2
	v_fmac_f32_e32 v104, v3, v3
	v_fmac_f32_e32 v105, v4, v4
	v_fmac_f32_e32 v106, v5, v5
	v_fmac_f32_e32 v103, v6, v6
	v_fmac_f32_e32 v104, v7, v7
	v_fmac_f32_e32 v105, v8, v8
	v_fmac_f32_e32 v106, v9, v9
	v_fmac_f32_e32 v103, v10, v10
	v_fmac_f32_e32 v104, v11, v11
	v_fmac_f32_e32 v105, v12, v12
	v_fmac_f32_e32 v106, v13, v13
	v_fmac_f32_e32 v103, v14, v14
	v_fmac_f32_e32 v104, v15, v15
	v_fmac_f32_e32 v105, v16, v16
	v_fmac_f32_e32 v106, v17, v17
	v_fmac_f32_e32 v103, v18, v18
	v_fmac_f32_e32 v104, v19, v19
	v_fmac_f32_e32 v105, v20, v20
	v_fmac_f32_e32 v106, v21, v21
	v_fmac_f32_e32 v103, v22, v22
	v_fmac_f32_e32 v104, v23, v23
	v_fmac_f32_e32 v105, v24, v24
	v_fmac_f32_e32 v106, v25, v25
	v_fmac_f32_e32 v103, v26, v26
	v_fmac_f32_e32 v104, v27, v27
	v_fmac_f32_e32 v105, v28, v28
	v_fmac_f32_e32 v106, v29, v29
	v_fmac_f32_e32 v103, v30, v30
	v_fmac_f32_e32 v104, v31, v31
	v_fmac_f32_e32 v105, v32, v32
	v_fmac_f32_e32 v106, v33, v33
	v_add_f32_e32 v103, v103, v104
	v_add_f32_e32 v105, v105, v106
	v_add_f32_e32 v103, v103, v105
	s_nop 1
	v_add_f32_dpp v103, v103, v103 quad_perm:[1,0,3,2] row_mask:0xf bank_mask:0xf
	s_nop 1
	v_add_f32_dpp v103, v103, v103 quad_perm:[2,3,0,1] row_mask:0xf bank_mask:0xf
	s_nop 1
	v_add_f32_dpp v103, v103, v103 row_half_mirror row_mask:0xf bank_mask:0xf
	s_nop 1
	v_add_f32_dpp v103, v103, v103 row_mirror row_mask:0xf bank_mask:0xf
	s_nop 1
	v_readlane_b32 s8, v103, 0
	v_readlane_b32 s9, v103, 16
	v_readlane_b32 s10, v103, 32
	v_readlane_b32 s11, v103, 48
	s_nop 1
	v_mov_b32_e32 v104, s8
	v_add_f32_e32 v104, s9, v104
	v_add_f32_e32 v104, s10, v104
	v_add_f32_e32 v104, s11, v104
	v_mov_b32_e32 v105, s17
	v_fma_f32 v104, v104, s16, v105
	v_rsq_f32_e32 v107, v104
	v_mul_f32_e32 v104, 0.5, v104
	v_mul_f32_e32 v105, v104, v107
	v_fma_f32 v105, -v105, v107, 0.5
	v_fma_f32 v107, v107, v105, v107
	v_mul_f32_e32 v2, v2, v107
	v_mul_f32_e32 v3, v3, v107
	v_mul_f32_e32 v4, v4, v107
	v_mul_f32_e32 v5, v5, v107
	v_mul_f32_e32 v6, v6, v107
	v_mul_f32_e32 v7, v7, v107
	v_mul_f32_e32 v8, v8, v107
	v_mul_f32_e32 v9, v9, v107
	v_mul_f32_e32 v10, v10, v107
	v_mul_f32_e32 v11, v11, v107
	v_mul_f32_e32 v12, v12, v107
	v_mul_f32_e32 v13, v13, v107
	v_mul_f32_e32 v14, v14, v107
	v_mul_f32_e32 v15, v15, v107
	v_mul_f32_e32 v16, v16, v107
	v_mul_f32_e32 v17, v17, v107
	v_mul_f32_e32 v18, v18, v107
	v_mul_f32_e32 v19, v19, v107
	v_mul_f32_e32 v20, v20, v107
	v_mul_f32_e32 v21, v21, v107
	v_mul_f32_e32 v22, v22, v107
	v_mul_f32_e32 v23, v23, v107
	v_mul_f32_e32 v24, v24, v107
	v_mul_f32_e32 v25, v25, v107
	v_mul_f32_e32 v26, v26, v107
	v_mul_f32_e32 v27, v27, v107
	v_mul_f32_e32 v28, v28, v107
	v_mul_f32_e32 v29, v29, v107
	v_mul_f32_e32 v30, v30, v107
	v_mul_f32_e32 v31, v31, v107
	v_mul_f32_e32 v32, v32, v107
	v_mul_f32_e32 v33, v33, v107
	s_lshl_b32 s5, s4, 12
	v_add_u32_e32 v103, s5, v102
	v_mul_f32_e32 v112, v2, v36
	v_mul_f32_e32 v35, v3, v37
	v_cvt_pk_bf16_f32 v108, v112, v35
	v_mul_f32_e32 v112, v4, v38
	v_mul_f32_e32 v35, v5, v39
	v_cvt_pk_bf16_f32 v109, v112, v35
	v_mul_f32_e32 v112, v6, v40
	v_mul_f32_e32 v35, v7, v41
	v_cvt_pk_bf16_f32 v110, v112, v35
	v_mul_f32_e32 v112, v8, v42
	v_mul_f32_e32 v35, v9, v43
	v_cvt_pk_bf16_f32 v111, v112, v35
	global_store_dwordx4 v103, v[108:111], s[2:3]
	v_mul_f32_e32 v112, v10, v44
	v_mul_f32_e32 v35, v11, v45
	v_cvt_pk_bf16_f32 v108, v112, v35
	v_mul_f32_e32 v112, v12, v46
	v_mul_f32_e32 v35, v13, v47
	v_cvt_pk_bf16_f32 v109, v112, v35
	v_mul_f32_e32 v112, v14, v48
; DI unsigned pk2(float lo, float hi) { return pg8::cvt_pk_bf16(lo, hi); }
; DI int lbid() { int b = (int)blockIdx.x; asm volatile("" : "+s"(b)); return b; }
; DI int lgdim() { int g = (int)gridDim.x; asm volatile("" : "+s"(g)); return g; }
; DI void prologue(const Params& P, LAS unsigned char* lds) {
;     ...
;             for (int j = 0; j < 8; ++j) { const f32x4 g = ((const f32x4*)(P.mem_norm_gain + i * D))[lane + 64 * j]; const f32x4 o = v[j] * rstd * g;
;                 v2u w; w.x = pk2(o.x, o.y); w.y = pk2(o.z, o.w); ((v2u*)(memn + ((size_t)i * MEMROWS + row) * D))[lane + 64 * j] = w; }
;     }
; DI void phase_rowpass0(const Params& P, int r) {
;     int tid_l = threadIdx.x; asm volatile("" : "+v"(tid_l)); const int lane = tid_l & 63, wave = tid_l >> 6;
;     bf16* X16 = (bf16*)(P.ws + WS_X16); float* RS = (float*)(P.ws + WS_RSTD); const float* xb = xin_row(P, r * MC);
;     const int NGW = lgdim() * 8;
;     for (int row = lbid() * 8 + wave; row < MC; row += 2 * NGW) {
;         const size_t o = (size_t)row * D;
;         if (row + NGW < MC) row_pass<false, true, 2, false, true>(xb + o, nullptr, X16 + o, RS + row, (size_t)NGW * D, NGW, nullptr, lane);
;         else row_pass<false, true, 1, false, true>(xb + o, nullptr, X16 + o, RS + row, 0, 0, nullptr, lane);
	v_mul_f32_e32 v35, v15, v49
	v_cvt_pk_bf16_f32 v110, v112, v35
	v_mul_f32_e32 v112, v16, v50
	v_mul_f32_e32 v35, v17, v51
	v_cvt_pk_bf16_f32 v111, v112, v35
	global_store_dwordx4 v103, v[108:111], s[2:3] offset:1024
	v_mul_f32_e32 v112, v18, v52
	v_mul_f32_e32 v35, v19, v53
	v_cvt_pk_bf16_f32 v108, v112, v35
	v_mul_f32_e32 v112, v20, v54
	v_mul_f32_e32 v35, v21, v55
	v_cvt_pk_bf16_f32 v109, v112, v35
	v_mul_f32_e32 v112, v22, v56
	v_mul_f32_e32 v35, v23, v57
	v_cvt_pk_bf16_f32 v110, v112, v35
	v_mul_f32_e32 v112, v24, v58
	v_mul_f32_e32 v35, v25, v59
	v_cvt_pk_bf16_f32 v111, v112, v35
	global_store_dwordx4 v103, v[108:111], s[2:3] offset:2048
	v_mul_f32_e32 v112, v26, v60
	v_mul_f32_e32 v35, v27, v61
	v_cvt_pk_bf16_f32 v108, v112, v35
	v_mul_f32_e32 v112, v28, v62
	v_mul_f32_e32 v35, v29, v63
	v_cvt_pk_bf16_f32 v109, v112, v35
	v_mul_f32_e32 v112, v30, v64
	v_mul_f32_e32 v35, v31, v65
	v_cvt_pk_bf16_f32 v110, v112, v35
	v_mul_f32_e32 v112, v32, v66
	v_mul_f32_e32 v35, v33, v67
	v_cvt_pk_bf16_f32 v111, v112, v35
	global_store_dwordx4 v103, v[108:111], s[2:3] offset:3072
	v_add_u32_e32 v103, 0x1400000, v103
	v_mul_f32_e32 v112, v2, v68
	v_mul_f32_e32 v35, v3, v69
	v_cvt_pk_bf16_f32 v108, v112, v35
	v_mul_f32_e32 v112, v4, v70
	v_mul_f32_e32 v35, v5, v71
	v_cvt_pk_bf16_f32 v109, v112, v35
	v_mul_f32_e32 v112, v6, v72
	v_mul_f32_e32 v35, v7, v73
	v_cvt_pk_bf16_f32 v110, v112, v35
	v_mul_f32_e32 v112, v8, v74
	v_mul_f32_e32 v35, v9, v75
	v_cvt_pk_bf16_f32 v111, v112, v35
	global_store_dwordx4 v103, v[108:111], s[2:3]
	v_mul_f32_e32 v112, v10, v76
	v_mul_f32_e32 v35, v11, v77
	v_cvt_pk_bf16_f32 v108, v112, v35
	v_mul_f32_e32 v112, v12, v78
	v_mul_f32_e32 v35, v13, v79
	v_cvt_pk_bf16_f32 v109, v112, v35
	v_mul_f32_e32 v112, v14, v80
	v_mul_f32_e32 v35, v15, v81
	v_cvt_pk_bf16_f32 v110, v112, v35
	v_mul_f32_e32 v112, v16, v82
	v_mul_f32_e32 v35, v17, v83
	v_cvt_pk_bf16_f32 v111, v112, v35
	global_store_dwordx4 v103, v[108:111], s[2:3] offset:1024
	v_mul_f32_e32 v112, v18, v84
	v_mul_f32_e32 v35, v19, v85
	v_cvt_pk_bf16_f32 v108, v112, v35
	v_mul_f32_e32 v112, v20, v86
	v_mul_f32_e32 v35, v21, v87
	v_cvt_pk_bf16_f32 v109, v112, v35
	v_mul_f32_e32 v112, v22, v88
	v_mul_f32_e32 v35, v23, v89
	v_cvt_pk_bf16_f32 v110, v112, v35
	v_mul_f32_e32 v112, v24, v90
	v_mul_f32_e32 v35, v25, v91
	v_cvt_pk_bf16_f32 v111, v112, v35
	global_store_dwordx4 v103, v[108:111], s[2:3] offset:2048
	v_mul_f32_e32 v112, v26, v92
	v_mul_f32_e32 v35, v27, v93
	v_cvt_pk_bf16_f32 v108, v112, v35
	v_mul_f32_e32 v112, v28, v94
	v_mul_f32_e32 v35, v29, v95
	v_cvt_pk_bf16_f32 v109, v112, v35
	v_mul_f32_e32 v112, v30, v96
	v_mul_f32_e32 v35, v31, v97
	v_cvt_pk_bf16_f32 v110, v112, v35
	v_mul_f32_e32 v112, v32, v98
	v_mul_f32_e32 v35, v33, v99
	v_cvt_pk_bf16_f32 v111, v112, v35
	global_store_dwordx4 v103, v[108:111], s[2:3] offset:3072
	s_add_i32 s4, s4, s34
	s_cmpk_lt_u32 s4, 0x1400
	s_cbranch_scc1 .Lmr_top
.LBB0_112:
	s_mov_b64 s[8:9], exec
	s_load_dwordx2 s[0:1], s[84:85], 0x0
	v_lshrrev_b32_e32 v12, 6, v152
	v_and_b32_e32 v2, 63, v152
	s_lshl_b32 s21, s64, 3
	v_readfirstlane_b32 s20, v12
	s_mov_b32 s24, 0x3a000000
	s_mov_b32 s25, 0x358637bd
	s_add_i32 s20, s21, s20
	s_lshl_b32 s21, s42, 3
	s_lshl_b32 s23, s21, 1
	s_add_i32 s22, s20, s21
	v_lshlrev_b32_e32 v3, 5, v2
	v_lshlrev_b32_e32 v2, 4, v2
	v_add_u32_e32 v4, 0x1000, v3
	s_waitcnt lgkmcnt(0)
	s_add_u32 s4, s54, 0x32700000
	s_addc_u32 s5, s55, 0
	s_add_u32 s6, s54, 0x10000
	s_addc_u32 s7, s55, 0
	s_lshl_b32 s26, s20, 13
	v_add_u32_e32 v96, s26, v3
	v_add_u32_e32 v97, s26, v4
	global_load_dwordx4 v[32:35], v96, s[0:1] nt
	global_load_dwordx4 v[36:39], v96, s[0:1] offset:16 nt
	global_load_dwordx4 v[40:43], v96, s[0:1] offset:2048 nt
	global_load_dwordx4 v[44:47], v96, s[0:1] offset:2064 nt
	global_load_dwordx4 v[48:51], v97, s[0:1] nt
	global_load_dwordx4 v[52:55], v97, s[0:1] offset:16 nt
	global_load_dwordx4 v[56:59], v97, s[0:1] offset:2048 nt
	global_load_dwordx4 v[60:63], v97, s[0:1] offset:2064 nt
	s_lshl_b32 s26, s22, 13
	v_add_u32_e32 v98, s26, v3
	v_add_u32_e32 v99, s26, v4
	global_load_dwordx4 v[64:67], v98, s[0:1] nt
	global_load_dwordx4 v[68:71], v98, s[0:1] offset:16 nt
	global_load_dwordx4 v[72:75], v98, s[0:1] offset:2048 nt
	global_load_dwordx4 v[76:79], v98, s[0:1] offset:2064 nt
	global_load_dwordx4 v[80:83], v99, s[0:1] nt
	global_load_dwordx4 v[84:87], v99, s[0:1] offset:16 nt
	global_load_dwordx4 v[88:91], v99, s[0:1] offset:2048 nt
	global_load_dwordx4 v[92:95], v99, s[0:1] offset:2064 nt
	s_waitcnt vmcnt(8)
; DI unsigned pk2(float lo, float hi) { return pg8::cvt_pk_bf16(lo, hi); }
; DI int lbid() { int b = (int)blockIdx.x; asm volatile("" : "+s"(b)); return b; }
; template <bool HAS_MIX, bool WRITE_H, int NR, bool SRC16, bool DST16>
; DI void row_pass(const void* xsrc, const bf16* mix, void* xdst, float* rsd, size_t rstride, int rsstride, const float* gpost, int lane) {
;     ...
;     if (!HAS_MIX && DST16) {
; #pragma unroll
;         for (int rr = 0; rr < NR; ++rr)
; #pragma unroll
;             for (int j = 0; j < 8; ++j) { v2u w; w.x = pk2(v[rr][j].x, v[rr][j].y); w.y = pk2(v[rr][j].z, v[rr][j].w); ((v2u*)((bf16*)xdst + rr * rstride))[lane + 64 * j] = w; }
;     }
;     if (HAS_MIX) {
;         float rstd[NR];
; #pragma unroll
;         for (int rr = 0; rr < NR; ++rr) { float ss = 0.f;
; #pragma unroll
;             for (int j = 0; j < 8; ++j) { const f32x4 m = bf4(mr[rr][j]); ss += (m.x * m.x + m.y * m.y) + (m.z * m.z + m.w * m.w); }
;             rstd[rr] = 1.0f / sqrtf(wave_sum(ss) * (1.0f / D) + EPS); }
; #pragma unroll
;         for (int j = 0; j < 8; ++j) { const f32x4 g = ((const f32x4*)gpost)[lane + 64 * j];
; #pragma unroll
;             for (int rr = 0; rr < NR; ++rr) { v[rr][j] = v[rr][j] + bf4(mr[rr][j]) * rstd[rr] * g;
;                 if (DST16) { v2u w; w.x = pk2(v[rr][j].x, v[rr][j].y); w.y = pk2(v[rr][j].z, v[rr][j].w); ((v2u*)((bf16*)xdst + rr * rstride))[lane + 64 * j] = w; }
;                 else __builtin_nontemporal_store(v[rr][j], (f32x4*)((float*)xdst + rr * rstride) + lane + 64 * j); } }
;     }
;     if (WRITE_H) {
; #pragma unroll
;         for (int rr = 0; rr < NR; ++rr) { float ss = 0.f;
; #pragma unroll
;             for (int j = 0; j < 8; ++j) ss += (v[rr][j].x * v[rr][j].x + v[rr][j].y * v[rr][j].y) + (v[rr][j].z * v[rr][j].z + v[rr][j].w * v[rr][j].w);
;             const float rstd = 1.0f / sqrtf(wave_sum(ss) * (1.0f / D) + EPS);
;             if (lane == 0) rsd[rr * rsstride] = rstd; }
; DI void phase_rowpass0(const Params& P, int r) {
;     ...
;     for (int row = lbid() * 8 + wave; row < MC; row += 2 * NGW) {
;         const size_t o = (size_t)row * D;
;         if (row + NGW < MC) row_pass<false, true, 2, false, true>(xb + o, nullptr, X16 + o, RS + row, (size_t)NGW * D, NGW, nullptr, lane);
;         else row_pass<false, true, 1, false, true>(xb + o, nullptr, X16 + o, RS + row, 0, 0, nullptr, lane);
.Lri_top:
	s_add_i32 s26, s20, s23
	s_cmpk_lt_u32 s26, 0x4000
	s_cbranch_scc0 .Lri_last
	s_waitcnt vmcnt(13)
	v_mov_b32_e32 v7, 0
	v_mov_b32_e32 v8, 0
	v_mov_b32_e32 v9, 0
	v_mov_b32_e32 v10, 0
	s_lshl_b32 s26, s20, 12
	v_add_u32_e32 v5, s26, v2
	v_fmac_f32_e32 v7, v32, v32
	v_fmac_f32_e32 v8, v33, v33
	v_fmac_f32_e32 v9, v34, v34
	v_fmac_f32_e32 v10, v35, v35
	v_fmac_f32_e32 v7, v36, v36
	v_fmac_f32_e32 v8, v37, v37
	v_fmac_f32_e32 v9, v38, v38
	v_fmac_f32_e32 v10, v39, v39
	v_cvt_pk_bf16_f32 v32, v32, v33
	v_cvt_pk_bf16_f32 v33, v34, v35
	v_cvt_pk_bf16_f32 v34, v36, v37
	v_cvt_pk_bf16_f32 v35, v38, v39
	global_store_dwordx4 v5, v[32:35], s[4:5]
	v_fmac_f32_e32 v7, v40, v40
	v_fmac_f32_e32 v8, v41, v41
	v_fmac_f32_e32 v9, v42, v42
	v_fmac_f32_e32 v10, v43, v43
	v_fmac_f32_e32 v7, v44, v44
	v_fmac_f32_e32 v8, v45, v45
	v_fmac_f32_e32 v9, v46, v46
	v_fmac_f32_e32 v10, v47, v47
	v_cvt_pk_bf16_f32 v40, v40, v41
	v_cvt_pk_bf16_f32 v41, v42, v43
	v_cvt_pk_bf16_f32 v42, v44, v45
	v_cvt_pk_bf16_f32 v43, v46, v47
	global_store_dwordx4 v5, v[40:43], s[4:5] offset:1024
	v_fmac_f32_e32 v7, v48, v48
	v_fmac_f32_e32 v8, v49, v49
	v_fmac_f32_e32 v9, v50, v50
	v_fmac_f32_e32 v10, v51, v51
	v_fmac_f32_e32 v7, v52, v52
	v_fmac_f32_e32 v8, v53, v53
	v_fmac_f32_e32 v9, v54, v54
	v_fmac_f32_e32 v10, v55, v55
	v_cvt_pk_bf16_f32 v48, v48, v49
	v_cvt_pk_bf16_f32 v49, v50, v51
	v_cvt_pk_bf16_f32 v50, v52, v53
	v_cvt_pk_bf16_f32 v51, v54, v55
	global_store_dwordx4 v5, v[48:51], s[4:5] offset:2048
	v_fmac_f32_e32 v7, v56, v56
	v_fmac_f32_e32 v8, v57, v57
	v_fmac_f32_e32 v9, v58, v58
	v_fmac_f32_e32 v10, v59, v59
	v_fmac_f32_e32 v7, v60, v60
	v_fmac_f32_e32 v8, v61, v61
	v_fmac_f32_e32 v9, v62, v62
	v_fmac_f32_e32 v10, v63, v63
	v_cvt_pk_bf16_f32 v56, v56, v57
	v_cvt_pk_bf16_f32 v57, v58, v59
	v_cvt_pk_bf16_f32 v58, v60, v61
	v_cvt_pk_bf16_f32 v59, v62, v63
	global_store_dwordx4 v5, v[56:59], s[4:5] offset:3072
	v_add_f32_e32 v7, v7, v8
	v_add_f32_e32 v9, v9, v10
	v_add_f32_e32 v7, v7, v9
	s_nop 1
	v_add_f32_dpp v7, v7, v7 quad_perm:[1,0,3,2] row_mask:0xf bank_mask:0xf
	s_nop 1
	v_add_f32_dpp v7, v7, v7 quad_perm:[2,3,0,1] row_mask:0xf bank_mask:0xf
	s_nop 1
	v_add_f32_dpp v7, v7, v7 row_half_mirror row_mask:0xf bank_mask:0xf
	s_nop 1
	v_add_f32_dpp v7, v7, v7 row_mirror row_mask:0xf bank_mask:0xf
	s_nop 1
	v_readlane_b32 s16, v7, 0
	v_readlane_b32 s17, v7, 16
	v_readlane_b32 s18, v7, 32
	v_readlane_b32 s19, v7, 48
	s_nop 1
	v_mov_b32_e32 v8, s16
	v_add_f32_e32 v8, s17, v8
	v_add_f32_e32 v8, s18, v8
	v_add_f32_e32 v8, s19, v8
	v_mov_b32_e32 v9, s25
	v_fma_f32 v8, v8, s24, v9
	v_rsq_f32_e32 v11, v8
	v_mul_f32_e32 v8, 0.5, v8
	v_mul_f32_e32 v9, v8, v11
	v_fma_f32 v9, -v9, v11, 0.5
	v_fma_f32 v11, v11, v9, v11
	s_lshl_b32 s26, s20, 2
	s_add_u32 s26, s6, s26
	s_addc_u32 s27, s7, 0
	v_mov_b32_e32 v10, 0
	s_mov_b64 exec, 1
	global_store_dword v10, v11, s[26:27]
	s_mov_b64 exec, -1
	s_add_i32 s20, s20, s23
	s_lshl_b32 s26, s20, 13
	v_add_u32_e32 v96, s26, v3
	v_add_u32_e32 v97, s26, v4
	global_load_dwordx4 v[32:35], v96, s[0:1] nt
	global_load_dwordx4 v[36:39], v96, s[0:1] offset:16 nt
	global_load_dwordx4 v[40:43], v96, s[0:1] offset:2048 nt
	global_load_dwordx4 v[44:47], v96, s[0:1] offset:2064 nt
	global_load_dwordx4 v[48:51], v97, s[0:1] nt
	global_load_dwordx4 v[52:55], v97, s[0:1] offset:16 nt
	global_load_dwordx4 v[56:59], v97, s[0:1] offset:2048 nt
	global_load_dwordx4 v[60:63], v97, s[0:1] offset:2064 nt
	s_waitcnt vmcnt(13)
	v_mov_b32_e32 v7, 0
	v_mov_b32_e32 v8, 0
	v_mov_b32_e32 v9, 0
	v_mov_b32_e32 v10, 0
	s_lshl_b32 s26, s22, 12
	v_add_u32_e32 v6, s26, v2
	v_fmac_f32_e32 v7, v64, v64
	v_fmac_f32_e32 v8, v65, v65
	v_fmac_f32_e32 v9, v66, v66
	v_fmac_f32_e32 v10, v67, v67
	v_fmac_f32_e32 v7, v68, v68
	v_fmac_f32_e32 v8, v69, v69
	v_fmac_f32_e32 v9, v70, v70
	v_fmac_f32_e32 v10, v71, v71
	v_cvt_pk_bf16_f32 v64, v64, v65
	v_cvt_pk_bf16_f32 v65, v66, v67
	v_cvt_pk_bf16_f32 v66, v68, v69
	v_cvt_pk_bf16_f32 v67, v70, v71
	global_store_dwordx4 v6, v[64:67], s[4:5]
	v_fmac_f32_e32 v7, v72, v72
	v_fmac_f32_e32 v8, v73, v73
	v_fmac_f32_e32 v9, v74, v74
	v_fmac_f32_e32 v10, v75, v75
	v_fmac_f32_e32 v7, v76, v76
	v_fmac_f32_e32 v8, v77, v77
	v_fmac_f32_e32 v9, v78, v78
	v_fmac_f32_e32 v10, v79, v79
	v_cvt_pk_bf16_f32 v72, v72, v73
	v_cvt_pk_bf16_f32 v73, v74, v75
	v_cvt_pk_bf16_f32 v74, v76, v77
	v_cvt_pk_bf16_f32 v75, v78, v79
	global_store_dwordx4 v6, v[72:75], s[4:5] offset:1024
	v_fmac_f32_e32 v7, v80, v80
	v_fmac_f32_e32 v8, v81, v81
	v_fmac_f32_e32 v9, v82, v82
	v_fmac_f32_e32 v10, v83, v83
	v_fmac_f32_e32 v7, v84, v84
	v_fmac_f32_e32 v8, v85, v85
	v_fmac_f32_e32 v9, v86, v86
	v_fmac_f32_e32 v10, v87, v87
	v_cvt_pk_bf16_f32 v80, v80, v81
	v_cvt_pk_bf16_f32 v81, v82, v83
	v_cvt_pk_bf16_f32 v82, v84, v85
	v_cvt_pk_bf16_f32 v83, v86, v87
	global_store_dwordx4 v6, v[80:83], s[4:5] offset:2048
	v_fmac_f32_e32 v7, v88, v88
	v_fmac_f32_e32 v8, v89, v89
	v_fmac_f32_e32 v9, v90, v90
	v_fmac_f32_e32 v10, v91, v91
	v_fmac_f32_e32 v7, v92, v92
	v_fmac_f32_e32 v8, v93, v93
	v_fmac_f32_e32 v9, v94, v94
	v_fmac_f32_e32 v10, v95, v95
	v_cvt_pk_bf16_f32 v88, v88, v89
	v_cvt_pk_bf16_f32 v89, v90, v91
	v_cvt_pk_bf16_f32 v90, v92, v93
	v_cvt_pk_bf16_f32 v91, v94, v95
	global_store_dwordx4 v6, v[88:91], s[4:5] offset:3072
	v_add_f32_e32 v7, v7, v8
	v_add_f32_e32 v9, v9, v10
	v_add_f32_e32 v7, v7, v9
	s_nop 1
	v_add_f32_dpp v7, v7, v7 quad_perm:[1,0,3,2] row_mask:0xf bank_mask:0xf
	s_nop 1
	v_add_f32_dpp v7, v7, v7 quad_perm:[2,3,0,1] row_mask:0xf bank_mask:0xf
	s_nop 1
	v_add_f32_dpp v7, v7, v7 row_half_mirror row_mask:0xf bank_mask:0xf
	s_nop 1
	v_add_f32_dpp v7, v7, v7 row_mirror row_mask:0xf bank_mask:0xf
	s_nop 1
	v_readlane_b32 s16, v7, 0
	v_readlane_b32 s17, v7, 16
	v_readlane_b32 s18, v7, 32
	v_readlane_b32 s19, v7, 48
	s_nop 1
	v_mov_b32_e32 v8, s16
	v_add_f32_e32 v8, s17, v8
	v_add_f32_e32 v8, s18, v8
	v_add_f32_e32 v8, s19, v8
	v_mov_b32_e32 v9, s25
	v_fma_f32 v8, v8, s24, v9
	v_rsq_f32_e32 v11, v8
	v_mul_f32_e32 v8, 0.5, v8
	v_mul_f32_e32 v9, v8, v11
	v_fma_f32 v9, -v9, v11, 0.5
	v_fma_f32 v11, v11, v9, v11
	s_lshl_b32 s26, s22, 2
	s_add_u32 s26, s6, s26
	s_addc_u32 s27, s7, 0
	v_mov_b32_e32 v10, 0
	s_mov_b64 exec, 1
	global_store_dword v10, v11, s[26:27]
	s_mov_b64 exec, -1
	s_add_i32 s22, s22, s23
	s_lshl_b32 s26, s22, 13
	v_add_u32_e32 v98, s26, v3
	v_add_u32_e32 v99, s26, v4
	global_load_dwordx4 v[64:67], v98, s[0:1] nt
	global_load_dwordx4 v[68:71], v98, s[0:1] offset:16 nt
	global_load_dwordx4 v[72:75], v98, s[0:1] offset:2048 nt
	global_load_dwordx4 v[76:79], v98, s[0:1] offset:2064 nt
	global_load_dwordx4 v[80:83], v99, s[0:1] nt
	global_load_dwordx4 v[84:87], v99, s[0:1] offset:16 nt
	global_load_dwordx4 v[88:91], v99, s[0:1] offset:2048 nt
	global_load_dwordx4 v[92:95], v99, s[0:1] offset:2064 nt
	s_branch .Lri_top
; DI unsigned pk2(float lo, float hi) { return pg8::cvt_pk_bf16(lo, hi); }
; DI int lbid() { int b = (int)blockIdx.x; asm volatile("" : "+s"(b)); return b; }
; template <bool HAS_MIX, bool WRITE_H, int NR, bool SRC16, bool DST16>
; DI void row_pass(const void* xsrc, const bf16* mix, void* xdst, float* rsd, size_t rstride, int rsstride, const float* gpost, int lane) {
;     ...
;     if (!HAS_MIX && DST16) {
; #pragma unroll
;         for (int rr = 0; rr < NR; ++rr)
; #pragma unroll
;             for (int j = 0; j < 8; ++j) { v2u w; w.x = pk2(v[rr][j].x, v[rr][j].y); w.y = pk2(v[rr][j].z, v[rr][j].w); ((v2u*)((bf16*)xdst + rr * rstride))[lane + 64 * j] = w; }
;     }
;     if (HAS_MIX) {
;         float rstd[NR];
; #pragma unroll
;         for (int rr = 0; rr < NR; ++rr) { float ss = 0.f;
; #pragma unroll
;             for (int j = 0; j < 8; ++j) { const f32x4 m = bf4(mr[rr][j]); ss += (m.x * m.x + m.y * m.y) + (m.z * m.z + m.w * m.w); }
;             rstd[rr] = 1.0f / sqrtf(wave_sum(ss) * (1.0f / D) + EPS); }
; #pragma unroll
;         for (int j = 0; j < 8; ++j) { const f32x4 g = ((const f32x4*)gpost)[lane + 64 * j];
; #pragma unroll
;             for (int rr = 0; rr < NR; ++rr) { v[rr][j] = v[rr][j] + bf4(mr[rr][j]) * rstd[rr] * g;
;                 if (DST16) { v2u w; w.x = pk2(v[rr][j].x, v[rr][j].y); w.y = pk2(v[rr][j].z, v[rr][j].w); ((v2u*)((bf16*)xdst + rr * rstride))[lane + 64 * j] = w; }
;                 else __builtin_nontemporal_store(v[rr][j], (f32x4*)((float*)xdst + rr * rstride) + lane + 64 * j); } }
;     }
;     if (WRITE_H) {
; #pragma unroll
;         for (int rr = 0; rr < NR; ++rr) { float ss = 0.f;
; #pragma unroll
;             for (int j = 0; j < 8; ++j) ss += (v[rr][j].x * v[rr][j].x + v[rr][j].y * v[rr][j].y) + (v[rr][j].z * v[rr][j].z + v[rr][j].w * v[rr][j].w);
;             const float rstd = 1.0f / sqrtf(wave_sum(ss) * (1.0f / D) + EPS);
;             if (lane == 0) rsd[rr * rsstride] = rstd; }
; DI void phase_rowpass0(const Params& P, int r) {
;     ...
;     for (int row = lbid() * 8 + wave; row < MC; row += 2 * NGW) {
;         const size_t o = (size_t)row * D;
;         if (row + NGW < MC) row_pass<false, true, 2, false, true>(xb + o, nullptr, X16 + o, RS + row, (size_t)NGW * D, NGW, nullptr, lane);
;         else row_pass<false, true, 1, false, true>(xb + o, nullptr, X16 + o, RS + row, 0, 0, nullptr, lane);
.Lri_last:
	s_waitcnt vmcnt(13)
	v_mov_b32_e32 v7, 0
	v_mov_b32_e32 v8, 0
	v_mov_b32_e32 v9, 0
	v_mov_b32_e32 v10, 0
	s_lshl_b32 s26, s20, 12
	v_add_u32_e32 v5, s26, v2
	v_fmac_f32_e32 v7, v32, v32
	v_fmac_f32_e32 v8, v33, v33
	v_fmac_f32_e32 v9, v34, v34
	v_fmac_f32_e32 v10, v35, v35
	v_fmac_f32_e32 v7, v36, v36
	v_fmac_f32_e32 v8, v37, v37
	v_fmac_f32_e32 v9, v38, v38
	v_fmac_f32_e32 v10, v39, v39
	v_cvt_pk_bf16_f32 v32, v32, v33
	v_cvt_pk_bf16_f32 v33, v34, v35
	v_cvt_pk_bf16_f32 v34, v36, v37
	v_cvt_pk_bf16_f32 v35, v38, v39
	global_store_dwordx4 v5, v[32:35], s[4:5]
	v_fmac_f32_e32 v7, v40, v40
	v_fmac_f32_e32 v8, v41, v41
	v_fmac_f32_e32 v9, v42, v42
	v_fmac_f32_e32 v10, v43, v43
	v_fmac_f32_e32 v7, v44, v44
	v_fmac_f32_e32 v8, v45, v45
	v_fmac_f32_e32 v9, v46, v46
	v_fmac_f32_e32 v10, v47, v47
	v_cvt_pk_bf16_f32 v40, v40, v41
	v_cvt_pk_bf16_f32 v41, v42, v43
	v_cvt_pk_bf16_f32 v42, v44, v45
	v_cvt_pk_bf16_f32 v43, v46, v47
	global_store_dwordx4 v5, v[40:43], s[4:5] offset:1024
	v_fmac_f32_e32 v7, v48, v48
	v_fmac_f32_e32 v8, v49, v49
	v_fmac_f32_e32 v9, v50, v50
	v_fmac_f32_e32 v10, v51, v51
	v_fmac_f32_e32 v7, v52, v52
	v_fmac_f32_e32 v8, v53, v53
	v_fmac_f32_e32 v9, v54, v54
	v_fmac_f32_e32 v10, v55, v55
	v_cvt_pk_bf16_f32 v48, v48, v49
	v_cvt_pk_bf16_f32 v49, v50, v51
	v_cvt_pk_bf16_f32 v50, v52, v53
	v_cvt_pk_bf16_f32 v51, v54, v55
	global_store_dwordx4 v5, v[48:51], s[4:5] offset:2048
	v_fmac_f32_e32 v7, v56, v56
	v_fmac_f32_e32 v8, v57, v57
	v_fmac_f32_e32 v9, v58, v58
	v_fmac_f32_e32 v10, v59, v59
	v_fmac_f32_e32 v7, v60, v60
	v_fmac_f32_e32 v8, v61, v61
	v_fmac_f32_e32 v9, v62, v62
	v_fmac_f32_e32 v10, v63, v63
	v_cvt_pk_bf16_f32 v56, v56, v57
	v_cvt_pk_bf16_f32 v57, v58, v59
	v_cvt_pk_bf16_f32 v58, v60, v61
	v_cvt_pk_bf16_f32 v59, v62, v63
	global_store_dwordx4 v5, v[56:59], s[4:5] offset:3072
	v_add_f32_e32 v7, v7, v8
	v_add_f32_e32 v9, v9, v10
	v_add_f32_e32 v7, v7, v9
	s_nop 1
	v_add_f32_dpp v7, v7, v7 quad_perm:[1,0,3,2] row_mask:0xf bank_mask:0xf
	s_nop 1
	v_add_f32_dpp v7, v7, v7 quad_perm:[2,3,0,1] row_mask:0xf bank_mask:0xf
	s_nop 1
	v_add_f32_dpp v7, v7, v7 row_half_mirror row_mask:0xf bank_mask:0xf
	s_nop 1
	v_add_f32_dpp v7, v7, v7 row_mirror row_mask:0xf bank_mask:0xf
	s_nop 1
	v_readlane_b32 s16, v7, 0
	v_readlane_b32 s17, v7, 16
	v_readlane_b32 s18, v7, 32
	v_readlane_b32 s19, v7, 48
	s_nop 1
	v_mov_b32_e32 v8, s16
	v_add_f32_e32 v8, s17, v8
	v_add_f32_e32 v8, s18, v8
	v_add_f32_e32 v8, s19, v8
	v_mov_b32_e32 v9, s25
	v_fma_f32 v8, v8, s24, v9
	v_rsq_f32_e32 v11, v8
	v_mul_f32_e32 v8, 0.5, v8
	v_mul_f32_e32 v9, v8, v11
	v_fma_f32 v9, -v9, v11, 0.5
	v_fma_f32 v11, v11, v9, v11
	s_lshl_b32 s26, s20, 2
	s_add_u32 s26, s6, s26
	s_addc_u32 s27, s7, 0
	v_mov_b32_e32 v10, 0
	s_mov_b64 exec, 1
	global_store_dword v10, v11, s[26:27]
	s_mov_b64 exec, -1
	s_waitcnt vmcnt(5)
	v_mov_b32_e32 v7, 0
	v_mov_b32_e32 v8, 0
	v_mov_b32_e32 v9, 0
	v_mov_b32_e32 v10, 0
	s_lshl_b32 s26, s22, 12
	v_add_u32_e32 v6, s26, v2
	v_fmac_f32_e32 v7, v64, v64
	v_fmac_f32_e32 v8, v65, v65
	v_fmac_f32_e32 v9, v66, v66
	v_fmac_f32_e32 v10, v67, v67
	v_fmac_f32_e32 v7, v68, v68
	v_fmac_f32_e32 v8, v69, v69
	v_fmac_f32_e32 v9, v70, v70
	v_fmac_f32_e32 v10, v71, v71
	v_cvt_pk_bf16_f32 v64, v64, v65
	v_cvt_pk_bf16_f32 v65, v66, v67
	v_cvt_pk_bf16_f32 v66, v68, v69
	v_cvt_pk_bf16_f32 v67, v70, v71
	global_store_dwordx4 v6, v[64:67], s[4:5]
	v_fmac_f32_e32 v7, v72, v72
	v_fmac_f32_e32 v8, v73, v73
	v_fmac_f32_e32 v9, v74, v74
	v_fmac_f32_e32 v10, v75, v75
	v_fmac_f32_e32 v7, v76, v76
	v_fmac_f32_e32 v8, v77, v77
	v_fmac_f32_e32 v9, v78, v78
	v_fmac_f32_e32 v10, v79, v79
	v_cvt_pk_bf16_f32 v72, v72, v73
	v_cvt_pk_bf16_f32 v73, v74, v75
	v_cvt_pk_bf16_f32 v74, v76, v77
	v_cvt_pk_bf16_f32 v75, v78, v79
	global_store_dwordx4 v6, v[72:75], s[4:5] offset:1024
	v_fmac_f32_e32 v7, v80, v80
	v_fmac_f32_e32 v8, v81, v81
	v_fmac_f32_e32 v9, v82, v82
	v_fmac_f32_e32 v10, v83, v83
	v_fmac_f32_e32 v7, v84, v84
	v_fmac_f32_e32 v8, v85, v85
	v_fmac_f32_e32 v9, v86, v86
	v_fmac_f32_e32 v10, v87, v87
	v_cvt_pk_bf16_f32 v80, v80, v81
	v_cvt_pk_bf16_f32 v81, v82, v83
	v_cvt_pk_bf16_f32 v82, v84, v85
	v_cvt_pk_bf16_f32 v83, v86, v87
	global_store_dwordx4 v6, v[80:83], s[4:5] offset:2048
	v_fmac_f32_e32 v7, v88, v88
	v_fmac_f32_e32 v8, v89, v89
	v_fmac_f32_e32 v9, v90, v90
	v_fmac_f32_e32 v10, v91, v91
	v_fmac_f32_e32 v7, v92, v92
	v_fmac_f32_e32 v8, v93, v93
	v_fmac_f32_e32 v9, v94, v94
	v_fmac_f32_e32 v10, v95, v95
	v_cvt_pk_bf16_f32 v88, v88, v89
	v_cvt_pk_bf16_f32 v89, v90, v91
	v_cvt_pk_bf16_f32 v90, v92, v93
	v_cvt_pk_bf16_f32 v91, v94, v95
	global_store_dwordx4 v6, v[88:91], s[4:5] offset:3072
	v_add_f32_e32 v7, v7, v8
	v_add_f32_e32 v9, v9, v10
	v_add_f32_e32 v7, v7, v9
	s_nop 1
	v_add_f32_dpp v7, v7, v7 quad_perm:[1,0,3,2] row_mask:0xf bank_mask:0xf
	s_nop 1
	v_add_f32_dpp v7, v7, v7 quad_perm:[2,3,0,1] row_mask:0xf bank_mask:0xf
	s_nop 1
	v_add_f32_dpp v7, v7, v7 row_half_mirror row_mask:0xf bank_mask:0xf
	s_nop 1
	v_add_f32_dpp v7, v7, v7 row_mirror row_mask:0xf bank_mask:0xf
	s_nop 1
	v_readlane_b32 s16, v7, 0
	v_readlane_b32 s17, v7, 16
	v_readlane_b32 s18, v7, 32
	v_readlane_b32 s19, v7, 48
	s_nop 1
	v_mov_b32_e32 v8, s16
	v_add_f32_e32 v8, s17, v8
	v_add_f32_e32 v8, s18, v8
	v_add_f32_e32 v8, s19, v8
	v_mov_b32_e32 v9, s25
	v_fma_f32 v8, v8, s24, v9
	v_rsq_f32_e32 v11, v8
	v_mul_f32_e32 v8, 0.5, v8
	v_mul_f32_e32 v9, v8, v11
	v_fma_f32 v9, -v9, v11, 0.5
	v_fma_f32 v11, v11, v9, v11
	s_lshl_b32 s26, s22, 2
	s_add_u32 s26, s6, s26
	s_addc_u32 s27, s7, 0
	v_mov_b32_e32 v10, 0
	s_mov_b64 exec, 1
	global_store_dword v10, v11, s[26:27]
	s_mov_b64 exec, -1
